# v12 + 16B merged bf16 stores (permlane16 swap) in the K=256 GEMM stream epilogue
# speedup vs baseline: 1.0322x; 1.0162x over previous
; __device__ __forceinline__ unsigned pk2(float lo, float hi) { f32x2_t v = {lo, hi}; bf16x2_t b = __builtin_convertvector(v, bf16x2_t); return __builtin_bit_cast(unsigned, b); }
;     __device__ __forceinline__ void operator()(const f32x4 (&acc)[2][2][4][2], const Unit& u, int wr, int wc, int fr, int fq) const {
;         const int row0 = u.pm * BM + wr * 64 + fr;
;         if (u.g == 1) {
; #pragma unroll
;             for (int ai = 0; ai < 2; ++ai)
; #pragma unroll
;                 for (int m = 0; m < 4; ++m) { const int row = row0 + ai * HALF + m * 16; const float* rp = rope + posidx(row) * 32 + 4 * fq; bf16_t* qp = Q + (size_t)row * QW;
; #pragma unroll
;                     for (int bj = 0; bj < 2; ++bj) { const int col32 = u.pn * BM + bj * HALF + wc * 32; f32x4 v0 = acc[ai][bj][m][0], v1 = acc[ai][bj][m][1];
;                         if ((col32 % 96) == 64) { const f32x4 c = *(const f32x4*)rp, s = *(const f32x4*)(rp + 16); const f32x4 o0 = v0 * c - v1 * s, o1 = v1 * c + v0 * s; v0 = o0; v1 = o1; }
;                         v0 = v0 * QSCALE; v1 = v1 * QSCALE;
;                         u32x2 w0, w1; w0.x = pk2(v0[0], v0[1]); w0.y = pk2(v0[2], v0[3]); w1.x = pk2(v1[0], v1[1]); w1.y = pk2(v1[2], v1[3]);
;                         *(u32x2*)(qp + col32 + 4 * fq) = w0; *(u32x2*)(qp + col32 + 16 + 4 * fq) = w1; } }
;         } else {
;             bf16_t* O = u.g == 0 ? KV : u.g == 2 ? MIX : QL; const int ldc = u.g == 0 ? 1024 : u.g == 2 ? DM : 2048; const float sc = u.g == 3 ? QSCALE : 1.f;
;             const int col0 = u.pn * BM + wc * 32 + 4 * fq;
.LBB0_905:
	s_lshl_b32 s12, s46, 8
	s_add_i32 s12, s12, s29
	v_mbcnt_lo_u32_b32 v130, -1, 0
	v_mbcnt_hi_u32_b32 v130, -1, v130
	v_and_b32_e32 v248, 16, v130
	v_lshrrev_b32_e32 v248, 4, v248
	v_mul_u32_u24_e32 v248, 24, v248
	v_mov_b32_e32 v249, 0
	s_cmp_lt_i32 s35, 1
	v_ashrrev_i32_e32 v144, 4, v130
	v_and_or_b32 v158, v130, 15, s12
	s_cbranch_scc1 .LBB0_909
	s_cmp_gt_i32 s35, 1
	s_cbranch_scc0 .LBB0_910
	s_mov_b64 s[92:93], -1
	s_mov_b64 s[12:13], 0
	s_cmp_eq_u32 s35, 2
	s_mov_b64 s[90:91], 0
	s_cbranch_scc0 .LBB0_911
	s_mov_b64 s[92:93], 0
	s_mov_b64 s[90:91], -1
	s_branch .LBB0_911

; __device__ __forceinline__ unsigned pk2(float lo, float hi) { f32x2_t v = {lo, hi}; bf16x2_t b = __builtin_convertvector(v, bf16x2_t); return __builtin_bit_cast(unsigned, b); }
;     __device__ __forceinline__ void operator()(const f32x4 (&acc)[2][2][4][2], const Unit& u, int wr, int wc, int fr, int fq) const {
;     ...
;         if (u.g == 1) {
; #pragma unroll
;             for (int ai = 0; ai < 2; ++ai)
; #pragma unroll
;                 for (int m = 0; m < 4; ++m) { const int row = row0 + ai * HALF + m * 16; const float* rp = rope + posidx(row) * 32 + 4 * fq; bf16_t* qp = Q + (size_t)row * QW;
; #pragma unroll
;                     for (int bj = 0; bj < 2; ++bj) { const int col32 = u.pn * BM + bj * HALF + wc * 32; f32x4 v0 = acc[ai][bj][m][0], v1 = acc[ai][bj][m][1];
;                         if ((col32 % 96) == 64) { const f32x4 c = *(const f32x4*)rp, s = *(const f32x4*)(rp + 16); const f32x4 o0 = v0 * c - v1 * s, o1 = v1 * c + v0 * s; v0 = o0; v1 = o1; }
;                         v0 = v0 * QSCALE; v1 = v1 * QSCALE;
;                         u32x2 w0, w1; w0.x = pk2(v0[0], v0[1]); w0.y = pk2(v0[2], v0[3]); w1.x = pk2(v1[0], v1[1]); w1.y = pk2(v1[2], v1[3]);
;                         *(u32x2*)(qp + col32 + 4 * fq) = w0; *(u32x2*)(qp + col32 + 16 + 4 * fq) = w1; } }
.LBB0_914:
	v_mov_b64_e32 v[142:143], s[66:67]
	v_mad_i64_i32 v[142:143], s[12:13], v158, s41, v[142:143]
	s_or_b32 s12, s94, 0x80
	s_mul_hi_i32 s13, s12, 0x2aaaaaab
	s_lshr_b32 s24, s13, 31
	s_lshr_b32 s13, s13, 4
	v_pk_mul_f32 v[132:133], v[132:133], s[80:81] op_sel_hi:[1,0]
	v_pk_mul_f32 v[130:131], v[130:131], s[80:81] op_sel_hi:[1,0]
	s_ashr_i32 s95, s94, 31
	s_add_i32 s13, s13, s24
	v_pk_mul_f32 v[136:137], v[136:137], s[80:81] op_sel_hi:[1,0]
	v_pk_mul_f32 v[134:135], v[134:135], s[80:81] op_sel_hi:[1,0]
	v_cvt_pk_bf16_f32 v130, v130, v131
	v_cvt_pk_bf16_f32 v131, v132, v133
	v_lshl_add_u64 v[132:133], s[94:95], 1, v[142:143]
	s_mulk_i32 s13, 0x60
	v_cvt_pk_bf16_f32 v134, v134, v135
	v_cvt_pk_bf16_f32 v135, v136, v137
	v_lshl_add_u64 v[142:143], v[138:139], 1, v[132:133]
	s_sub_i32 s12, s12, s13
	v_mov_b32_e32 v240, v134
	v_mov_b32_e32 v241, v135
	v_mov_b32_e32 v242, v130
	v_mov_b32_e32 v243, v131
	s_nop 1
	v_permlane16_swap_b32_e32 v240, v242
	v_permlane16_swap_b32_e32 v241, v243
	v_lshl_add_u64 v[238:239], v[142:143], 0, v[248:249]
	global_store_dwordx4 v[238:239], v[240:243], off
	s_cmp_eq_u32 s12, 64
	v_mov_b64_e32 v[132:133], v[92:93]
	v_mov_b64_e32 v[136:137], v[96:97]
	s_cselect_b64 s[96:97], -1, 0
	s_cmp_lg_u32 s12, 64
	v_mov_b64_e32 v[130:131], v[90:91]
	v_mov_b64_e32 v[134:135], v[94:95]
	s_cbranch_scc1 .LBB0_916
	global_load_dwordx4 v[130:133], v[140:141], off offset:64
	global_load_dwordx4 v[160:163], v[140:141], off
	s_waitcnt vmcnt(0)
	v_pk_mul_f32 v[134:135], v[92:93], v[132:133]
	v_pk_mul_f32 v[140:141], v[90:91], v[130:131]
	v_pk_mul_f32 v[132:133], v[96:97], v[132:133]
	v_pk_mul_f32 v[130:131], v[94:95], v[130:131]
	v_pk_fma_f32 v[136:137], v[96:97], v[162:163], v[134:135] neg_lo:[0,0,1] neg_hi:[0,0,1]
	v_pk_fma_f32 v[134:135], v[94:95], v[160:161], v[140:141] neg_lo:[0,0,1] neg_hi:[0,0,1]
	v_pk_fma_f32 v[132:133], v[92:93], v[162:163], v[132:133]
	v_pk_fma_f32 v[130:131], v[90:91], v[160:161], v[130:131]
.LBB0_916:
	v_pk_mul_f32 v[136:137], v[136:137], s[80:81] op_sel_hi:[1,0]
	v_pk_mul_f32 v[134:135], v[134:135], s[80:81] op_sel_hi:[1,0]
	v_pk_mul_f32 v[132:133], v[132:133], s[80:81] op_sel_hi:[1,0]
	v_pk_mul_f32 v[130:131], v[130:131], s[80:81] op_sel_hi:[1,0]
	v_cvt_pk_bf16_f32 v134, v134, v135
	v_cvt_pk_bf16_f32 v135, v136, v137
	v_cvt_pk_bf16_f32 v130, v130, v131
	v_cvt_pk_bf16_f32 v131, v132, v133
	v_mov_b32_e32 v244, v134
	v_mov_b32_e32 v245, v135
	v_mov_b32_e32 v246, v130
	v_mov_b32_e32 v247, v131
	s_nop 1
	v_permlane16_swap_b32_e32 v244, v246
	v_permlane16_swap_b32_e32 v245, v247
	v_lshl_add_u64 v[234:235], v[142:143], 0, v[248:249]
	global_store_dwordx4 v[234:235], v[244:247], off offset:256
	v_or_b32_e32 v142, 16, v158
	s_movk_i32 s12, 0x7df
	v_bitop3_b32 v130, v158, s12, 16 bitop3:0xc8
	v_cmp_gt_i32_e32 vcc, s34, v142
	v_mov_b64_e32 v[136:137], v[120:121]
	v_mov_b64_e32 v[134:135], v[118:119]
	v_cndmask_b32_e32 v130, v145, v130, vcc
	v_lshlrev_b32_e32 v150, 7, v130
	v_lshl_add_u64 v[130:131], s[68:69], 0, v[150:151]
	v_lshl_add_u64 v[140:141], v[138:139], 2, v[130:131]
	v_cndmask_b32_e64 v130, 0, 1, s[14:15]
	v_cmp_ne_u32_e64 s[12:13], 1, v130
	v_mov_b64_e32 v[132:133], v[116:117]
	s_andn2_b64 vcc, exec, s[14:15]
	v_mov_b64_e32 v[130:131], v[114:115]
	s_cbranch_vccnz .LBB0_918
	global_load_dwordx4 v[130:133], v[140:141], off offset:64
	global_load_dwordx4 v[160:163], v[140:141], off
	s_waitcnt vmcnt(0)
	v_pk_mul_f32 v[134:135], v[116:117], v[132:133]
	v_pk_mul_f32 v[170:171], v[114:115], v[130:131]
	v_pk_mul_f32 v[132:133], v[120:121], v[132:133]
	v_pk_mul_f32 v[130:131], v[118:119], v[130:131]
	v_pk_fma_f32 v[136:137], v[120:121], v[162:163], v[134:135] neg_lo:[0,0,1] neg_hi:[0,0,1]
	v_pk_fma_f32 v[134:135], v[118:119], v[160:161], v[170:171] neg_lo:[0,0,1] neg_hi:[0,0,1]
	v_pk_fma_f32 v[132:133], v[116:117], v[162:163], v[132:133]
	v_pk_fma_f32 v[130:131], v[114:115], v[160:161], v[130:131]
.LBB0_918:
	v_mov_b64_e32 v[160:161], s[66:67]
	v_mad_i64_i32 v[142:143], s[14:15], v142, s41, v[160:161]
	v_pk_mul_f32 v[132:133], v[132:133], s[80:81] op_sel_hi:[1,0]
	v_pk_mul_f32 v[130:131], v[130:131], s[80:81] op_sel_hi:[1,0]
	v_pk_mul_f32 v[136:137], v[136:137], s[80:81] op_sel_hi:[1,0]
	v_pk_mul_f32 v[134:135], v[134:135], s[80:81] op_sel_hi:[1,0]
	v_cvt_pk_bf16_f32 v130, v130, v131
	v_cvt_pk_bf16_f32 v131, v132, v133
	v_lshl_add_u64 v[132:133], s[94:95], 1, v[142:143]
	v_cvt_pk_bf16_f32 v134, v134, v135
	v_cvt_pk_bf16_f32 v135, v136, v137
	v_lshl_add_u64 v[142:143], v[138:139], 1, v[132:133]
	v_mov_b32_e32 v226, v134
	v_mov_b32_e32 v227, v135
	v_mov_b32_e32 v228, v130
	v_mov_b32_e32 v229, v131
	s_nop 1
	v_permlane16_swap_b32_e32 v226, v228
	v_permlane16_swap_b32_e32 v227, v229
	v_lshl_add_u64 v[224:225], v[142:143], 0, v[248:249]
	global_store_dwordx4 v[224:225], v[226:229], off
	v_cndmask_b32_e64 v130, 0, 1, s[96:97]
	v_cmp_ne_u32_e64 s[14:15], 1, v130
	v_mov_b64_e32 v[132:133], v[84:85]
	v_mov_b64_e32 v[136:137], v[88:89]
	s_andn2_b64 vcc, exec, s[96:97]
	v_mov_b64_e32 v[130:131], v[82:83]
	v_mov_b64_e32 v[134:135], v[86:87]
	s_cbranch_vccnz .LBB0_920
	global_load_dwordx4 v[130:133], v[140:141], off offset:64
	global_load_dwordx4 v[160:163], v[140:141], off
	s_waitcnt vmcnt(0)
	v_pk_mul_f32 v[134:135], v[84:85], v[132:133]
	v_pk_mul_f32 v[140:141], v[82:83], v[130:131]
	v_pk_mul_f32 v[132:133], v[88:89], v[132:133]
	v_pk_mul_f32 v[130:131], v[86:87], v[130:131]
	v_pk_fma_f32 v[136:137], v[88:89], v[162:163], v[134:135] neg_lo:[0,0,1] neg_hi:[0,0,1]
	v_pk_fma_f32 v[134:135], v[86:87], v[160:161], v[140:141] neg_lo:[0,0,1] neg_hi:[0,0,1]
	v_pk_fma_f32 v[132:133], v[84:85], v[162:163], v[132:133]
	v_pk_fma_f32 v[130:131], v[82:83], v[160:161], v[130:131]
; __device__ __forceinline__ unsigned pk2(float lo, float hi) { f32x2_t v = {lo, hi}; bf16x2_t b = __builtin_convertvector(v, bf16x2_t); return __builtin_bit_cast(unsigned, b); }
;     __device__ __forceinline__ void operator()(const f32x4 (&acc)[2][2][4][2], const Unit& u, int wr, int wc, int fr, int fq) const {
;     ...
;         if (u.g == 1) {
; #pragma unroll
;             for (int ai = 0; ai < 2; ++ai)
; #pragma unroll
;                 for (int m = 0; m < 4; ++m) { const int row = row0 + ai * HALF + m * 16; const float* rp = rope + posidx(row) * 32 + 4 * fq; bf16_t* qp = Q + (size_t)row * QW;
; #pragma unroll
;                     for (int bj = 0; bj < 2; ++bj) { const int col32 = u.pn * BM + bj * HALF + wc * 32; f32x4 v0 = acc[ai][bj][m][0], v1 = acc[ai][bj][m][1];
;                         if ((col32 % 96) == 64) { const f32x4 c = *(const f32x4*)rp, s = *(const f32x4*)(rp + 16); const f32x4 o0 = v0 * c - v1 * s, o1 = v1 * c + v0 * s; v0 = o0; v1 = o1; }
;                         v0 = v0 * QSCALE; v1 = v1 * QSCALE;
;                         u32x2 w0, w1; w0.x = pk2(v0[0], v0[1]); w0.y = pk2(v0[2], v0[3]); w1.x = pk2(v1[0], v1[1]); w1.y = pk2(v1[2], v1[3]);
;                         *(u32x2*)(qp + col32 + 4 * fq) = w0; *(u32x2*)(qp + col32 + 16 + 4 * fq) = w1; } }
.LBB0_920:
	v_pk_mul_f32 v[136:137], v[136:137], s[80:81] op_sel_hi:[1,0]
	v_pk_mul_f32 v[134:135], v[134:135], s[80:81] op_sel_hi:[1,0]
	v_pk_mul_f32 v[132:133], v[132:133], s[80:81] op_sel_hi:[1,0]
	v_pk_mul_f32 v[130:131], v[130:131], s[80:81] op_sel_hi:[1,0]
	v_cvt_pk_bf16_f32 v134, v134, v135
	v_cvt_pk_bf16_f32 v135, v136, v137
	v_cvt_pk_bf16_f32 v130, v130, v131
	v_cvt_pk_bf16_f32 v131, v132, v133
	v_mov_b32_e32 v230, v134
	v_mov_b32_e32 v231, v135
	v_mov_b32_e32 v232, v130
	v_mov_b32_e32 v233, v131
	s_nop 1
	v_permlane16_swap_b32_e32 v230, v232
	v_permlane16_swap_b32_e32 v231, v233
	v_lshl_add_u64 v[222:223], v[142:143], 0, v[248:249]
	global_store_dwordx4 v[222:223], v[230:233], off offset:256
	v_or_b32_e32 v142, 32, v158
	s_movk_i32 s24, 0x7ef
	v_bitop3_b32 v130, v158, s24, 32 bitop3:0xc8
	v_cmp_gt_i32_e32 vcc, s34, v142
	v_mov_b64_e32 v[136:137], v[112:113]
	v_mov_b64_e32 v[134:135], v[110:111]
	v_cndmask_b32_e32 v130, v145, v130, vcc
	v_lshlrev_b32_e32 v150, 7, v130
	v_lshl_add_u64 v[130:131], s[68:69], 0, v[150:151]
	v_lshl_add_u64 v[140:141], v[138:139], 2, v[130:131]
	v_mov_b64_e32 v[132:133], v[108:109]
	s_and_b64 vcc, exec, s[12:13]
	v_mov_b64_e32 v[130:131], v[106:107]
	s_cbranch_vccnz .LBB0_922
	global_load_dwordx4 v[130:133], v[140:141], off offset:64
	global_load_dwordx4 v[160:163], v[140:141], off
	s_waitcnt vmcnt(0)
	v_pk_mul_f32 v[134:135], v[108:109], v[132:133]
	v_pk_mul_f32 v[170:171], v[106:107], v[130:131]
	v_pk_mul_f32 v[132:133], v[112:113], v[132:133]
	v_pk_mul_f32 v[130:131], v[110:111], v[130:131]
	v_pk_fma_f32 v[136:137], v[112:113], v[162:163], v[134:135] neg_lo:[0,0,1] neg_hi:[0,0,1]
	v_pk_fma_f32 v[134:135], v[110:111], v[160:161], v[170:171] neg_lo:[0,0,1] neg_hi:[0,0,1]
	v_pk_fma_f32 v[132:133], v[108:109], v[162:163], v[132:133]
	v_pk_fma_f32 v[130:131], v[106:107], v[160:161], v[130:131]
.LBB0_922:
	v_mov_b64_e32 v[160:161], s[66:67]
	v_mad_i64_i32 v[142:143], s[24:25], v142, s41, v[160:161]
	v_pk_mul_f32 v[132:133], v[132:133], s[80:81] op_sel_hi:[1,0]
	v_pk_mul_f32 v[130:131], v[130:131], s[80:81] op_sel_hi:[1,0]
	v_pk_mul_f32 v[136:137], v[136:137], s[80:81] op_sel_hi:[1,0]
	v_pk_mul_f32 v[134:135], v[134:135], s[80:81] op_sel_hi:[1,0]
	v_cvt_pk_bf16_f32 v130, v130, v131
	v_cvt_pk_bf16_f32 v131, v132, v133
	v_lshl_add_u64 v[132:133], s[94:95], 1, v[142:143]
	v_cvt_pk_bf16_f32 v134, v134, v135
	v_cvt_pk_bf16_f32 v135, v136, v137
	v_lshl_add_u64 v[142:143], v[138:139], 1, v[132:133]
	v_mov_b32_e32 v240, v134
	v_mov_b32_e32 v241, v135
	v_mov_b32_e32 v242, v130
	v_mov_b32_e32 v243, v131
	s_nop 1
	v_permlane16_swap_b32_e32 v240, v242
	v_permlane16_swap_b32_e32 v241, v243
	v_lshl_add_u64 v[238:239], v[142:143], 0, v[248:249]
	global_store_dwordx4 v[238:239], v[240:243], off
	v_mov_b64_e32 v[132:133], v[76:77]
	v_mov_b64_e32 v[136:137], v[80:81]
	s_and_b64 vcc, exec, s[14:15]
	v_mov_b64_e32 v[130:131], v[74:75]
	v_mov_b64_e32 v[134:135], v[78:79]
	s_cbranch_vccnz .LBB0_924
	global_load_dwordx4 v[130:133], v[140:141], off offset:64
	global_load_dwordx4 v[160:163], v[140:141], off
	s_waitcnt vmcnt(0)
	v_pk_mul_f32 v[134:135], v[76:77], v[132:133]
	v_pk_mul_f32 v[140:141], v[74:75], v[130:131]
	v_pk_mul_f32 v[132:133], v[80:81], v[132:133]
	v_pk_mul_f32 v[130:131], v[78:79], v[130:131]
	v_pk_fma_f32 v[136:137], v[80:81], v[162:163], v[134:135] neg_lo:[0,0,1] neg_hi:[0,0,1]
	v_pk_fma_f32 v[134:135], v[78:79], v[160:161], v[140:141] neg_lo:[0,0,1] neg_hi:[0,0,1]
	v_pk_fma_f32 v[132:133], v[76:77], v[162:163], v[132:133]
	v_pk_fma_f32 v[130:131], v[74:75], v[160:161], v[130:131]
.LBB0_924:
	v_pk_mul_f32 v[136:137], v[136:137], s[80:81] op_sel_hi:[1,0]
	v_pk_mul_f32 v[134:135], v[134:135], s[80:81] op_sel_hi:[1,0]
	v_pk_mul_f32 v[132:133], v[132:133], s[80:81] op_sel_hi:[1,0]
	v_pk_mul_f32 v[130:131], v[130:131], s[80:81] op_sel_hi:[1,0]
	v_cvt_pk_bf16_f32 v134, v134, v135
	v_cvt_pk_bf16_f32 v135, v136, v137
	v_cvt_pk_bf16_f32 v130, v130, v131
	v_cvt_pk_bf16_f32 v131, v132, v133
	v_mov_b32_e32 v244, v134
	v_mov_b32_e32 v245, v135
	v_mov_b32_e32 v246, v130
	v_mov_b32_e32 v247, v131
	s_nop 1
	v_permlane16_swap_b32_e32 v244, v246
	v_permlane16_swap_b32_e32 v245, v247
	v_lshl_add_u64 v[234:235], v[142:143], 0, v[248:249]
	global_store_dwordx4 v[234:235], v[244:247], off offset:256
	v_or_b32_e32 v142, 48, v158
	s_movk_i32 s24, 0x7ff
	v_bitop3_b32 v130, v158, s24, 48 bitop3:0xc8
	v_cmp_gt_i32_e32 vcc, s34, v142
	v_mov_b64_e32 v[136:137], v[104:105]
	v_mov_b64_e32 v[134:135], v[102:103]
	v_cndmask_b32_e32 v130, v145, v130, vcc
	v_lshlrev_b32_e32 v150, 7, v130
	v_lshl_add_u64 v[130:131], s[68:69], 0, v[150:151]
	v_lshl_add_u64 v[140:141], v[138:139], 2, v[130:131]
	v_mov_b64_e32 v[132:133], v[100:101]
	s_and_b64 vcc, exec, s[12:13]
	v_mov_b64_e32 v[130:131], v[98:99]
	s_cbranch_vccnz .LBB0_926
	global_load_dwordx4 v[130:133], v[140:141], off offset:64
	global_load_dwordx4 v[160:163], v[140:141], off
	s_waitcnt vmcnt(0)
	v_pk_mul_f32 v[134:135], v[100:101], v[132:133]
	v_pk_mul_f32 v[170:171], v[98:99], v[130:131]
	v_pk_mul_f32 v[132:133], v[104:105], v[132:133]
	v_pk_mul_f32 v[130:131], v[102:103], v[130:131]
	v_pk_fma_f32 v[136:137], v[104:105], v[162:163], v[134:135] neg_lo:[0,0,1] neg_hi:[0,0,1]
	v_pk_fma_f32 v[134:135], v[102:103], v[160:161], v[170:171] neg_lo:[0,0,1] neg_hi:[0,0,1]
	v_pk_fma_f32 v[132:133], v[100:101], v[162:163], v[132:133]
	v_pk_fma_f32 v[130:131], v[98:99], v[160:161], v[130:131]
; __device__ __forceinline__ unsigned pk2(float lo, float hi) { f32x2_t v = {lo, hi}; bf16x2_t b = __builtin_convertvector(v, bf16x2_t); return __builtin_bit_cast(unsigned, b); }
;     __device__ __forceinline__ void operator()(const f32x4 (&acc)[2][2][4][2], const Unit& u, int wr, int wc, int fr, int fq) const {
;     ...
;         if (u.g == 1) {
; #pragma unroll
;             for (int ai = 0; ai < 2; ++ai)
; #pragma unroll
;                 for (int m = 0; m < 4; ++m) { const int row = row0 + ai * HALF + m * 16; const float* rp = rope + posidx(row) * 32 + 4 * fq; bf16_t* qp = Q + (size_t)row * QW;
; #pragma unroll
;                     for (int bj = 0; bj < 2; ++bj) { const int col32 = u.pn * BM + bj * HALF + wc * 32; f32x4 v0 = acc[ai][bj][m][0], v1 = acc[ai][bj][m][1];
;                         if ((col32 % 96) == 64) { const f32x4 c = *(const f32x4*)rp, s = *(const f32x4*)(rp + 16); const f32x4 o0 = v0 * c - v1 * s, o1 = v1 * c + v0 * s; v0 = o0; v1 = o1; }
;                         v0 = v0 * QSCALE; v1 = v1 * QSCALE;
;                         u32x2 w0, w1; w0.x = pk2(v0[0], v0[1]); w0.y = pk2(v0[2], v0[3]); w1.x = pk2(v1[0], v1[1]); w1.y = pk2(v1[2], v1[3]);
;                         *(u32x2*)(qp + col32 + 4 * fq) = w0; *(u32x2*)(qp + col32 + 16 + 4 * fq) = w1; } }
.LBB0_926:
	v_mov_b64_e32 v[160:161], s[66:67]
	v_mad_i64_i32 v[142:143], s[24:25], v142, s41, v[160:161]
	v_pk_mul_f32 v[132:133], v[132:133], s[80:81] op_sel_hi:[1,0]
	v_pk_mul_f32 v[130:131], v[130:131], s[80:81] op_sel_hi:[1,0]
	v_pk_mul_f32 v[136:137], v[136:137], s[80:81] op_sel_hi:[1,0]
	v_pk_mul_f32 v[134:135], v[134:135], s[80:81] op_sel_hi:[1,0]
	v_cvt_pk_bf16_f32 v130, v130, v131
	v_cvt_pk_bf16_f32 v131, v132, v133
	v_lshl_add_u64 v[132:133], s[94:95], 1, v[142:143]
	v_cvt_pk_bf16_f32 v134, v134, v135
	v_cvt_pk_bf16_f32 v135, v136, v137
	v_lshl_add_u64 v[142:143], v[138:139], 1, v[132:133]
	v_mov_b32_e32 v226, v134
	v_mov_b32_e32 v227, v135
	v_mov_b32_e32 v228, v130
	v_mov_b32_e32 v229, v131
	s_nop 1
	v_permlane16_swap_b32_e32 v226, v228
	v_permlane16_swap_b32_e32 v227, v229
	v_lshl_add_u64 v[224:225], v[142:143], 0, v[248:249]
	global_store_dwordx4 v[224:225], v[226:229], off
	v_mov_b64_e32 v[132:133], v[68:69]
	v_mov_b64_e32 v[136:137], v[72:73]
	s_and_b64 vcc, exec, s[14:15]
	v_mov_b64_e32 v[130:131], v[66:67]
	v_mov_b64_e32 v[134:135], v[70:71]
	s_cbranch_vccnz .LBB0_928
	global_load_dwordx4 v[130:133], v[140:141], off offset:64
	global_load_dwordx4 v[160:163], v[140:141], off
	s_waitcnt vmcnt(0)
	v_pk_mul_f32 v[134:135], v[68:69], v[132:133]
	v_pk_mul_f32 v[140:141], v[66:67], v[130:131]
	v_pk_mul_f32 v[132:133], v[72:73], v[132:133]
	v_pk_mul_f32 v[130:131], v[70:71], v[130:131]
	v_pk_fma_f32 v[136:137], v[72:73], v[162:163], v[134:135] neg_lo:[0,0,1] neg_hi:[0,0,1]
	v_pk_fma_f32 v[134:135], v[70:71], v[160:161], v[140:141] neg_lo:[0,0,1] neg_hi:[0,0,1]
	v_pk_fma_f32 v[132:133], v[68:69], v[162:163], v[132:133]
	v_pk_fma_f32 v[130:131], v[66:67], v[160:161], v[130:131]
.LBB0_928:
	v_pk_mul_f32 v[136:137], v[136:137], s[80:81] op_sel_hi:[1,0]
	v_pk_mul_f32 v[134:135], v[134:135], s[80:81] op_sel_hi:[1,0]
	v_pk_mul_f32 v[132:133], v[132:133], s[80:81] op_sel_hi:[1,0]
	v_pk_mul_f32 v[130:131], v[130:131], s[80:81] op_sel_hi:[1,0]
	v_cvt_pk_bf16_f32 v134, v134, v135
	v_cvt_pk_bf16_f32 v135, v136, v137
	v_cvt_pk_bf16_f32 v130, v130, v131
	v_cvt_pk_bf16_f32 v131, v132, v133
	v_mov_b32_e32 v230, v134
	v_mov_b32_e32 v231, v135
	v_mov_b32_e32 v232, v130
	v_mov_b32_e32 v233, v131
	s_nop 1
	v_permlane16_swap_b32_e32 v230, v232
	v_permlane16_swap_b32_e32 v231, v233
	v_lshl_add_u64 v[222:223], v[142:143], 0, v[248:249]
	global_store_dwordx4 v[222:223], v[230:233], off offset:256
	v_add_u32_e32 v142, 0x80, v158
	s_movk_i32 s24, 0x7f80
	v_and_b32_e32 v130, 0x7cf, v142
	v_cmp_gt_i32_e32 vcc, s24, v158
	v_mov_b64_e32 v[136:137], v[64:65]
	v_mov_b64_e32 v[134:135], v[62:63]
	v_cndmask_b32_e32 v130, v145, v130, vcc
	v_lshlrev_b32_e32 v150, 7, v130
	v_lshl_add_u64 v[130:131], s[68:69], 0, v[150:151]
	v_lshl_add_u64 v[140:141], v[138:139], 2, v[130:131]
	v_mov_b64_e32 v[132:133], v[60:61]
	s_and_b64 vcc, exec, s[12:13]
	v_mov_b64_e32 v[130:131], v[58:59]
	s_cbranch_vccnz .LBB0_930
	global_load_dwordx4 v[130:133], v[140:141], off offset:64
	global_load_dwordx4 v[160:163], v[140:141], off
	s_waitcnt vmcnt(0)
	v_pk_mul_f32 v[134:135], v[60:61], v[132:133]
	v_pk_mul_f32 v[170:171], v[58:59], v[130:131]
	v_pk_mul_f32 v[132:133], v[64:65], v[132:133]
	v_pk_mul_f32 v[130:131], v[62:63], v[130:131]
	v_pk_fma_f32 v[136:137], v[64:65], v[162:163], v[134:135] neg_lo:[0,0,1] neg_hi:[0,0,1]
	v_pk_fma_f32 v[134:135], v[62:63], v[160:161], v[170:171] neg_lo:[0,0,1] neg_hi:[0,0,1]
	v_pk_fma_f32 v[132:133], v[60:61], v[162:163], v[132:133]
	v_pk_fma_f32 v[130:131], v[58:59], v[160:161], v[130:131]
.LBB0_930:
	v_mov_b64_e32 v[160:161], s[66:67]
	v_mad_i64_i32 v[142:143], s[24:25], v142, s41, v[160:161]
	v_pk_mul_f32 v[132:133], v[132:133], s[80:81] op_sel_hi:[1,0]
	v_pk_mul_f32 v[130:131], v[130:131], s[80:81] op_sel_hi:[1,0]
	v_pk_mul_f32 v[136:137], v[136:137], s[80:81] op_sel_hi:[1,0]
	v_pk_mul_f32 v[134:135], v[134:135], s[80:81] op_sel_hi:[1,0]
	v_cvt_pk_bf16_f32 v130, v130, v131
	v_cvt_pk_bf16_f32 v131, v132, v133
	v_lshl_add_u64 v[132:133], s[94:95], 1, v[142:143]
	v_cvt_pk_bf16_f32 v134, v134, v135
	v_cvt_pk_bf16_f32 v135, v136, v137
	v_lshl_add_u64 v[142:143], v[138:139], 1, v[132:133]
	v_mov_b32_e32 v240, v134
	v_mov_b32_e32 v241, v135
	v_mov_b32_e32 v242, v130
	v_mov_b32_e32 v243, v131
	s_nop 1
	v_permlane16_swap_b32_e32 v240, v242
	v_permlane16_swap_b32_e32 v241, v243
	v_lshl_add_u64 v[238:239], v[142:143], 0, v[248:249]
	global_store_dwordx4 v[238:239], v[240:243], off
	v_mov_b64_e32 v[132:133], v[28:29]
	v_mov_b64_e32 v[136:137], v[32:33]
	s_and_b64 vcc, exec, s[14:15]
	v_mov_b64_e32 v[130:131], v[26:27]
	v_mov_b64_e32 v[134:135], v[30:31]
	s_cbranch_vccnz .LBB0_932
	global_load_dwordx4 v[130:133], v[140:141], off offset:64
	global_load_dwordx4 v[160:163], v[140:141], off
	s_waitcnt vmcnt(0)
	v_pk_mul_f32 v[134:135], v[28:29], v[132:133]
	v_pk_mul_f32 v[140:141], v[26:27], v[130:131]
	v_pk_mul_f32 v[132:133], v[32:33], v[132:133]
	v_pk_mul_f32 v[130:131], v[30:31], v[130:131]
	v_pk_fma_f32 v[136:137], v[32:33], v[162:163], v[134:135] neg_lo:[0,0,1] neg_hi:[0,0,1]
	v_pk_fma_f32 v[134:135], v[30:31], v[160:161], v[140:141] neg_lo:[0,0,1] neg_hi:[0,0,1]
	v_pk_fma_f32 v[132:133], v[28:29], v[162:163], v[132:133]
	v_pk_fma_f32 v[130:131], v[26:27], v[160:161], v[130:131]
; __device__ __forceinline__ unsigned pk2(float lo, float hi) { f32x2_t v = {lo, hi}; bf16x2_t b = __builtin_convertvector(v, bf16x2_t); return __builtin_bit_cast(unsigned, b); }
;     __device__ __forceinline__ void operator()(const f32x4 (&acc)[2][2][4][2], const Unit& u, int wr, int wc, int fr, int fq) const {
;     ...
;         if (u.g == 1) {
; #pragma unroll
;             for (int ai = 0; ai < 2; ++ai)
; #pragma unroll
;                 for (int m = 0; m < 4; ++m) { const int row = row0 + ai * HALF + m * 16; const float* rp = rope + posidx(row) * 32 + 4 * fq; bf16_t* qp = Q + (size_t)row * QW;
; #pragma unroll
;                     for (int bj = 0; bj < 2; ++bj) { const int col32 = u.pn * BM + bj * HALF + wc * 32; f32x4 v0 = acc[ai][bj][m][0], v1 = acc[ai][bj][m][1];
;                         if ((col32 % 96) == 64) { const f32x4 c = *(const f32x4*)rp, s = *(const f32x4*)(rp + 16); const f32x4 o0 = v0 * c - v1 * s, o1 = v1 * c + v0 * s; v0 = o0; v1 = o1; }
;                         v0 = v0 * QSCALE; v1 = v1 * QSCALE;
;                         u32x2 w0, w1; w0.x = pk2(v0[0], v0[1]); w0.y = pk2(v0[2], v0[3]); w1.x = pk2(v1[0], v1[1]); w1.y = pk2(v1[2], v1[3]);
;                         *(u32x2*)(qp + col32 + 4 * fq) = w0; *(u32x2*)(qp + col32 + 16 + 4 * fq) = w1; } }
.LBB0_932:
	v_pk_mul_f32 v[136:137], v[136:137], s[80:81] op_sel_hi:[1,0]
	v_pk_mul_f32 v[134:135], v[134:135], s[80:81] op_sel_hi:[1,0]
	v_pk_mul_f32 v[132:133], v[132:133], s[80:81] op_sel_hi:[1,0]
	v_pk_mul_f32 v[130:131], v[130:131], s[80:81] op_sel_hi:[1,0]
	v_cvt_pk_bf16_f32 v134, v134, v135
	v_cvt_pk_bf16_f32 v135, v136, v137
	v_cvt_pk_bf16_f32 v130, v130, v131
	v_cvt_pk_bf16_f32 v131, v132, v133
	v_mov_b32_e32 v244, v134
	v_mov_b32_e32 v245, v135
	v_mov_b32_e32 v246, v130
	v_mov_b32_e32 v247, v131
	s_nop 1
	v_permlane16_swap_b32_e32 v244, v246
	v_permlane16_swap_b32_e32 v245, v247
	v_lshl_add_u64 v[234:235], v[142:143], 0, v[248:249]
	global_store_dwordx4 v[234:235], v[244:247], off offset:256
	v_add_u32_e32 v142, 0x90, v158
	s_movk_i32 s24, 0x7f70
	v_and_b32_e32 v130, 0x7df, v142
	v_cmp_gt_i32_e32 vcc, s24, v158
	v_mov_b64_e32 v[136:137], v[56:57]
	v_mov_b64_e32 v[134:135], v[54:55]
	v_cndmask_b32_e32 v130, v145, v130, vcc
	v_lshlrev_b32_e32 v150, 7, v130
	v_lshl_add_u64 v[130:131], s[68:69], 0, v[150:151]
	v_lshl_add_u64 v[140:141], v[138:139], 2, v[130:131]
	v_mov_b64_e32 v[132:133], v[52:53]
	s_and_b64 vcc, exec, s[12:13]
	v_mov_b64_e32 v[130:131], v[50:51]
	s_cbranch_vccnz .LBB0_934
	global_load_dwordx4 v[130:133], v[140:141], off offset:64
	global_load_dwordx4 v[160:163], v[140:141], off
	s_waitcnt vmcnt(0)
	v_pk_mul_f32 v[134:135], v[52:53], v[132:133]
	v_pk_mul_f32 v[170:171], v[50:51], v[130:131]
	v_pk_mul_f32 v[132:133], v[56:57], v[132:133]
	v_pk_mul_f32 v[130:131], v[54:55], v[130:131]
	v_pk_fma_f32 v[136:137], v[56:57], v[162:163], v[134:135] neg_lo:[0,0,1] neg_hi:[0,0,1]
	v_pk_fma_f32 v[134:135], v[54:55], v[160:161], v[170:171] neg_lo:[0,0,1] neg_hi:[0,0,1]
	v_pk_fma_f32 v[132:133], v[52:53], v[162:163], v[132:133]
	v_pk_fma_f32 v[130:131], v[50:51], v[160:161], v[130:131]
.LBB0_934:
	v_mov_b64_e32 v[160:161], s[66:67]
	v_mad_i64_i32 v[142:143], s[24:25], v142, s41, v[160:161]
	v_pk_mul_f32 v[132:133], v[132:133], s[80:81] op_sel_hi:[1,0]
	v_pk_mul_f32 v[130:131], v[130:131], s[80:81] op_sel_hi:[1,0]
	v_pk_mul_f32 v[136:137], v[136:137], s[80:81] op_sel_hi:[1,0]
	v_pk_mul_f32 v[134:135], v[134:135], s[80:81] op_sel_hi:[1,0]
	v_cvt_pk_bf16_f32 v130, v130, v131
	v_cvt_pk_bf16_f32 v131, v132, v133
	v_lshl_add_u64 v[132:133], s[94:95], 1, v[142:143]
	v_cvt_pk_bf16_f32 v134, v134, v135
	v_cvt_pk_bf16_f32 v135, v136, v137
	v_lshl_add_u64 v[142:143], v[138:139], 1, v[132:133]
	v_mov_b32_e32 v226, v134
	v_mov_b32_e32 v227, v135
	v_mov_b32_e32 v228, v130
	v_mov_b32_e32 v229, v131
	s_nop 1
	v_permlane16_swap_b32_e32 v226, v228
	v_permlane16_swap_b32_e32 v227, v229
	v_lshl_add_u64 v[224:225], v[142:143], 0, v[248:249]
	global_store_dwordx4 v[224:225], v[226:229], off
	v_mov_b64_e32 v[132:133], v[20:21]
	v_mov_b64_e32 v[136:137], v[24:25]
	s_and_b64 vcc, exec, s[14:15]
	v_mov_b64_e32 v[130:131], v[18:19]
	v_mov_b64_e32 v[134:135], v[22:23]
	s_cbranch_vccnz .LBB0_936
	global_load_dwordx4 v[130:133], v[140:141], off offset:64
	global_load_dwordx4 v[160:163], v[140:141], off
	s_waitcnt vmcnt(0)
	v_pk_mul_f32 v[134:135], v[20:21], v[132:133]
	v_pk_mul_f32 v[140:141], v[18:19], v[130:131]
	v_pk_mul_f32 v[132:133], v[24:25], v[132:133]
	v_pk_mul_f32 v[130:131], v[22:23], v[130:131]
	v_pk_fma_f32 v[136:137], v[24:25], v[162:163], v[134:135] neg_lo:[0,0,1] neg_hi:[0,0,1]
	v_pk_fma_f32 v[134:135], v[22:23], v[160:161], v[140:141] neg_lo:[0,0,1] neg_hi:[0,0,1]
	v_pk_fma_f32 v[132:133], v[20:21], v[162:163], v[132:133]
	v_pk_fma_f32 v[130:131], v[18:19], v[160:161], v[130:131]
.LBB0_936:
	v_pk_mul_f32 v[136:137], v[136:137], s[80:81] op_sel_hi:[1,0]
	v_pk_mul_f32 v[134:135], v[134:135], s[80:81] op_sel_hi:[1,0]
	v_pk_mul_f32 v[132:133], v[132:133], s[80:81] op_sel_hi:[1,0]
	v_pk_mul_f32 v[130:131], v[130:131], s[80:81] op_sel_hi:[1,0]
	v_cvt_pk_bf16_f32 v134, v134, v135
	v_cvt_pk_bf16_f32 v135, v136, v137
	v_cvt_pk_bf16_f32 v130, v130, v131
	v_cvt_pk_bf16_f32 v131, v132, v133
	v_mov_b32_e32 v230, v134
	v_mov_b32_e32 v231, v135
	v_mov_b32_e32 v232, v130
	v_mov_b32_e32 v233, v131
	s_nop 1
	v_permlane16_swap_b32_e32 v230, v232
	v_permlane16_swap_b32_e32 v231, v233
	v_lshl_add_u64 v[222:223], v[142:143], 0, v[248:249]
	global_store_dwordx4 v[222:223], v[230:233], off offset:256
	v_add_u32_e32 v142, 0xa0, v158
	s_movk_i32 s24, 0x7f60
	v_and_b32_e32 v130, 0x7ef, v142
	v_cmp_gt_i32_e32 vcc, s24, v158
	v_mov_b64_e32 v[136:137], v[48:49]
	v_mov_b64_e32 v[134:135], v[46:47]
	v_cndmask_b32_e32 v130, v145, v130, vcc
	v_lshlrev_b32_e32 v150, 7, v130
	v_lshl_add_u64 v[130:131], s[68:69], 0, v[150:151]
	v_lshl_add_u64 v[140:141], v[138:139], 2, v[130:131]
	v_mov_b64_e32 v[132:133], v[44:45]
	s_and_b64 vcc, exec, s[12:13]
	v_mov_b64_e32 v[130:131], v[42:43]
	s_cbranch_vccnz .LBB0_938
	global_load_dwordx4 v[130:133], v[140:141], off offset:64
	global_load_dwordx4 v[160:163], v[140:141], off
	s_waitcnt vmcnt(0)
	v_pk_mul_f32 v[134:135], v[44:45], v[132:133]
	v_pk_mul_f32 v[170:171], v[42:43], v[130:131]
	v_pk_mul_f32 v[132:133], v[48:49], v[132:133]
	v_pk_mul_f32 v[130:131], v[46:47], v[130:131]
	v_pk_fma_f32 v[136:137], v[48:49], v[162:163], v[134:135] neg_lo:[0,0,1] neg_hi:[0,0,1]
	v_pk_fma_f32 v[134:135], v[46:47], v[160:161], v[170:171] neg_lo:[0,0,1] neg_hi:[0,0,1]
	v_pk_fma_f32 v[132:133], v[44:45], v[162:163], v[132:133]
	v_pk_fma_f32 v[130:131], v[42:43], v[160:161], v[130:131]
; __device__ __forceinline__ unsigned pk2(float lo, float hi) { f32x2_t v = {lo, hi}; bf16x2_t b = __builtin_convertvector(v, bf16x2_t); return __builtin_bit_cast(unsigned, b); }
;     __device__ __forceinline__ void operator()(const f32x4 (&acc)[2][2][4][2], const Unit& u, int wr, int wc, int fr, int fq) const {
;     ...
;         if (u.g == 1) {
; #pragma unroll
;             for (int ai = 0; ai < 2; ++ai)
; #pragma unroll
;                 for (int m = 0; m < 4; ++m) { const int row = row0 + ai * HALF + m * 16; const float* rp = rope + posidx(row) * 32 + 4 * fq; bf16_t* qp = Q + (size_t)row * QW;
; #pragma unroll
;                     for (int bj = 0; bj < 2; ++bj) { const int col32 = u.pn * BM + bj * HALF + wc * 32; f32x4 v0 = acc[ai][bj][m][0], v1 = acc[ai][bj][m][1];
;                         if ((col32 % 96) == 64) { const f32x4 c = *(const f32x4*)rp, s = *(const f32x4*)(rp + 16); const f32x4 o0 = v0 * c - v1 * s, o1 = v1 * c + v0 * s; v0 = o0; v1 = o1; }
;                         v0 = v0 * QSCALE; v1 = v1 * QSCALE;
;                         u32x2 w0, w1; w0.x = pk2(v0[0], v0[1]); w0.y = pk2(v0[2], v0[3]); w1.x = pk2(v1[0], v1[1]); w1.y = pk2(v1[2], v1[3]);
;                         *(u32x2*)(qp + col32 + 4 * fq) = w0; *(u32x2*)(qp + col32 + 16 + 4 * fq) = w1; } }
.LBB0_938:
	v_mov_b64_e32 v[160:161], s[66:67]
	v_mad_i64_i32 v[142:143], s[24:25], v142, s41, v[160:161]
	v_pk_mul_f32 v[132:133], v[132:133], s[80:81] op_sel_hi:[1,0]
	v_pk_mul_f32 v[130:131], v[130:131], s[80:81] op_sel_hi:[1,0]
	v_pk_mul_f32 v[136:137], v[136:137], s[80:81] op_sel_hi:[1,0]
	v_pk_mul_f32 v[134:135], v[134:135], s[80:81] op_sel_hi:[1,0]
	v_cvt_pk_bf16_f32 v130, v130, v131
	v_cvt_pk_bf16_f32 v131, v132, v133
	v_lshl_add_u64 v[132:133], s[94:95], 1, v[142:143]
	v_cvt_pk_bf16_f32 v134, v134, v135
	v_cvt_pk_bf16_f32 v135, v136, v137
	v_lshl_add_u64 v[142:143], v[138:139], 1, v[132:133]
	v_mov_b32_e32 v240, v134
	v_mov_b32_e32 v241, v135
	v_mov_b32_e32 v242, v130
	v_mov_b32_e32 v243, v131
	s_nop 1
	v_permlane16_swap_b32_e32 v240, v242
	v_permlane16_swap_b32_e32 v241, v243
	v_lshl_add_u64 v[238:239], v[142:143], 0, v[248:249]
	global_store_dwordx4 v[238:239], v[240:243], off
	v_mov_b64_e32 v[132:133], v[12:13]
	v_mov_b64_e32 v[136:137], v[16:17]
	s_and_b64 vcc, exec, s[14:15]
	v_mov_b64_e32 v[130:131], v[10:11]
	v_mov_b64_e32 v[134:135], v[14:15]
	s_cbranch_vccnz .LBB0_940
	global_load_dwordx4 v[130:133], v[140:141], off offset:64
	global_load_dwordx4 v[160:163], v[140:141], off
	s_waitcnt vmcnt(0)
	v_pk_mul_f32 v[134:135], v[12:13], v[132:133]
	v_pk_mul_f32 v[140:141], v[10:11], v[130:131]
	v_pk_mul_f32 v[132:133], v[16:17], v[132:133]
	v_pk_mul_f32 v[130:131], v[14:15], v[130:131]
	v_pk_fma_f32 v[136:137], v[16:17], v[162:163], v[134:135] neg_lo:[0,0,1] neg_hi:[0,0,1]
	v_pk_fma_f32 v[134:135], v[14:15], v[160:161], v[140:141] neg_lo:[0,0,1] neg_hi:[0,0,1]
	v_pk_fma_f32 v[132:133], v[12:13], v[162:163], v[132:133]
	v_pk_fma_f32 v[130:131], v[10:11], v[160:161], v[130:131]
.LBB0_940:
	v_pk_mul_f32 v[136:137], v[136:137], s[80:81] op_sel_hi:[1,0]
	v_pk_mul_f32 v[134:135], v[134:135], s[80:81] op_sel_hi:[1,0]
	v_pk_mul_f32 v[132:133], v[132:133], s[80:81] op_sel_hi:[1,0]
	v_pk_mul_f32 v[130:131], v[130:131], s[80:81] op_sel_hi:[1,0]
	v_cvt_pk_bf16_f32 v134, v134, v135
	v_cvt_pk_bf16_f32 v135, v136, v137
	v_cvt_pk_bf16_f32 v130, v130, v131
	v_cvt_pk_bf16_f32 v131, v132, v133
	v_mov_b32_e32 v244, v134
	v_mov_b32_e32 v245, v135
	v_mov_b32_e32 v246, v130
	v_mov_b32_e32 v247, v131
	s_nop 1
	v_permlane16_swap_b32_e32 v244, v246
	v_permlane16_swap_b32_e32 v245, v247
	v_lshl_add_u64 v[234:235], v[142:143], 0, v[248:249]
	global_store_dwordx4 v[234:235], v[244:247], off offset:256
	v_add_u32_e32 v142, 0xb0, v158
	s_movk_i32 s24, 0x7f50
	v_and_b32_e32 v130, 0x7ff, v142
	v_cmp_gt_i32_e32 vcc, s24, v158
	v_mov_b64_e32 v[136:137], v[40:41]
	v_mov_b64_e32 v[134:135], v[38:39]
	v_cndmask_b32_e32 v130, v145, v130, vcc
	v_lshlrev_b32_e32 v150, 7, v130
	v_lshl_add_u64 v[130:131], s[68:69], 0, v[150:151]
	v_lshl_add_u64 v[140:141], v[138:139], 2, v[130:131]
	v_mov_b64_e32 v[132:133], v[36:37]
	s_and_b64 vcc, exec, s[12:13]
	v_mov_b64_e32 v[130:131], v[34:35]
	s_cbranch_vccnz .LBB0_942
	global_load_dwordx4 v[130:133], v[140:141], off offset:64
	global_load_dwordx4 v[160:163], v[140:141], off
	s_waitcnt vmcnt(0)
	v_pk_mul_f32 v[134:135], v[36:37], v[132:133]
	v_pk_mul_f32 v[170:171], v[34:35], v[130:131]
	v_pk_mul_f32 v[132:133], v[40:41], v[132:133]
	v_pk_mul_f32 v[130:131], v[38:39], v[130:131]
	v_pk_fma_f32 v[136:137], v[40:41], v[162:163], v[134:135] neg_lo:[0,0,1] neg_hi:[0,0,1]
	v_pk_fma_f32 v[134:135], v[38:39], v[160:161], v[170:171] neg_lo:[0,0,1] neg_hi:[0,0,1]
	v_pk_fma_f32 v[132:133], v[36:37], v[162:163], v[132:133]
	v_pk_fma_f32 v[130:131], v[34:35], v[160:161], v[130:131]
.LBB0_942:
	v_mov_b64_e32 v[160:161], s[66:67]
	v_mad_i64_i32 v[142:143], s[12:13], v142, s41, v[160:161]
	v_pk_mul_f32 v[132:133], v[132:133], s[80:81] op_sel_hi:[1,0]
	v_pk_mul_f32 v[130:131], v[130:131], s[80:81] op_sel_hi:[1,0]
	v_pk_mul_f32 v[136:137], v[136:137], s[80:81] op_sel_hi:[1,0]
	v_pk_mul_f32 v[134:135], v[134:135], s[80:81] op_sel_hi:[1,0]
	v_cvt_pk_bf16_f32 v130, v130, v131
	v_cvt_pk_bf16_f32 v131, v132, v133
	v_lshl_add_u64 v[132:133], s[94:95], 1, v[142:143]
	v_cvt_pk_bf16_f32 v134, v134, v135
	v_cvt_pk_bf16_f32 v135, v136, v137
	v_lshl_add_u64 v[138:139], v[138:139], 1, v[132:133]
	v_mov_b32_e32 v226, v134
	v_mov_b32_e32 v227, v135
	v_mov_b32_e32 v228, v130
	v_mov_b32_e32 v229, v131
	s_nop 1
	v_permlane16_swap_b32_e32 v226, v228
	v_permlane16_swap_b32_e32 v227, v229
	v_lshl_add_u64 v[224:225], v[138:139], 0, v[248:249]
	global_store_dwordx4 v[224:225], v[226:229], off
	v_mov_b64_e32 v[132:133], v[4:5]
	v_mov_b64_e32 v[136:137], v[8:9]
	s_and_b64 vcc, exec, s[14:15]
	v_mov_b64_e32 v[130:131], v[2:3]
	v_mov_b64_e32 v[134:135], v[6:7]
	s_cbranch_vccnz .LBB0_944
	global_load_dwordx4 v[130:133], v[140:141], off offset:64
	s_nop 0
	global_load_dwordx4 v[140:143], v[140:141], off
	s_waitcnt vmcnt(0)
	v_pk_mul_f32 v[134:135], v[4:5], v[132:133]
	v_pk_mul_f32 v[160:161], v[2:3], v[130:131]
	v_pk_mul_f32 v[132:133], v[8:9], v[132:133]
	v_pk_mul_f32 v[130:131], v[6:7], v[130:131]
	v_pk_fma_f32 v[136:137], v[8:9], v[142:143], v[134:135] neg_lo:[0,0,1] neg_hi:[0,0,1]
	v_pk_fma_f32 v[134:135], v[6:7], v[140:141], v[160:161] neg_lo:[0,0,1] neg_hi:[0,0,1]
	v_pk_fma_f32 v[132:133], v[4:5], v[142:143], v[132:133]
	v_pk_fma_f32 v[130:131], v[2:3], v[140:141], v[130:131]
.LBB0_944:
	v_pk_mul_f32 v[136:137], v[136:137], s[80:81] op_sel_hi:[1,0]
	v_pk_mul_f32 v[134:135], v[134:135], s[80:81] op_sel_hi:[1,0]
	v_pk_mul_f32 v[132:133], v[132:133], s[80:81] op_sel_hi:[1,0]
	v_pk_mul_f32 v[130:131], v[130:131], s[80:81] op_sel_hi:[1,0]
	v_cvt_pk_bf16_f32 v134, v134, v135
	v_cvt_pk_bf16_f32 v135, v136, v137
	v_cvt_pk_bf16_f32 v130, v130, v131
	v_cvt_pk_bf16_f32 v131, v132, v133
	v_mov_b32_e32 v230, v134
	v_mov_b32_e32 v231, v135
	v_mov_b32_e32 v232, v130
	v_mov_b32_e32 v233, v131
	s_nop 1
	v_permlane16_swap_b32_e32 v230, v232
	v_permlane16_swap_b32_e32 v231, v233
	v_lshl_add_u64 v[222:223], v[138:139], 0, v[248:249]
	global_store_dwordx4 v[222:223], v[230:233], off offset:256

; __device__ __forceinline__ unsigned pk2(float lo, float hi) { f32x2_t v = {lo, hi}; bf16x2_t b = __builtin_convertvector(v, bf16x2_t); return __builtin_bit_cast(unsigned, b); }
;     __device__ __forceinline__ void operator()(const f32x4 (&acc)[2][2][4][2], const Unit& u, int wr, int wc, int fr, int fq) const {
;     ...
;         } else {
;             bf16_t* O = u.g == 0 ? KV : u.g == 2 ? MIX : QL; const int ldc = u.g == 0 ? 1024 : u.g == 2 ? DM : 2048; const float sc = u.g == 3 ? QSCALE : 1.f;
;             const int col0 = u.pn * BM + wc * 32 + 4 * fq;
;             f32x4 sv[2][2];
; #pragma unroll
;             for (int bj = 0; bj < 2; ++bj)
; #pragma unroll
;                 for (int n = 0; n < 2; ++n) { sv[bj][n] = (f32x4){sc, sc, sc, sc}; if (u.g == 2) sv[bj][n] = *(const f32x4*)(pool_scale + col0 + bj * HALF + n * 16); }
; #pragma unroll
;             for (int ai = 0; ai < 2; ++ai)
; #pragma unroll
;                 for (int m = 0; m < 4; ++m) { bf16_t* rowp = O + (size_t)(row0 + ai * HALF + m * 16) * ldc + col0;
; #pragma unroll
;                     for (int bj = 0; bj < 2; ++bj)
; #pragma unroll
;                         for (int n = 0; n < 2; ++n) { const f32x4 v = acc[ai][bj][m][n] * sv[bj][n]; u32x2 w; w.x = pk2(v[0], v[1]); w.y = pk2(v[2], v[3]); *(u32x2*)(rowp + bj * HALF + n * 16) = w; } }
.LBB0_959:
	s_cmp_eq_u32 s35, 0
	s_cselect_b64 s[12:13], -1, 0
	s_or_b64 s[12:13], s[12:13], s[90:91]
	s_and_b64 s[12:13], s[12:13], exec
	v_ashrrev_i32_e32 v159, 31, v158
	s_cselect_b32 s12, 10, 11
	v_lshl_add_u64 v[160:161], v[160:161], 1, s[14:15]
	v_lshlrev_b64 v[162:163], s12, v[158:159]
	s_waitcnt vmcnt(0)
	v_pk_mul_f32 v[170:171], v[128:129], v[136:137]
	v_pk_mul_f32 v[172:173], v[126:127], v[134:135]
	v_lshl_add_u64 v[162:163], v[162:163], 1, v[160:161]
	v_cvt_pk_bf16_f32 v172, v172, v173
	v_cvt_pk_bf16_f32 v173, v170, v171
	v_mov_b32_e32 v240, v172
	v_mov_b32_e32 v241, v173
	v_pk_mul_f32 v[170:171], v[124:125], v[140:141]
	v_pk_mul_f32 v[172:173], v[122:123], v[138:139]
	s_nop 0
	v_cvt_pk_bf16_f32 v172, v172, v173
	v_cvt_pk_bf16_f32 v173, v170, v171
	v_mov_b32_e32 v242, v172
	v_mov_b32_e32 v243, v173
	s_nop 1
	v_permlane16_swap_b32_e32 v240, v242
	v_permlane16_swap_b32_e32 v241, v243
	v_lshl_add_u64 v[238:239], v[162:163], 0, v[248:249]
	global_store_dwordx4 v[238:239], v[240:243], off
	v_pk_mul_f32 v[170:171], v[96:97], v[144:145]
	v_pk_mul_f32 v[172:173], v[94:95], v[142:143]
	s_nop 0
	v_cvt_pk_bf16_f32 v172, v172, v173
	v_cvt_pk_bf16_f32 v173, v170, v171
	v_mov_b32_e32 v244, v172
	v_mov_b32_e32 v245, v173
	v_pk_mul_f32 v[170:171], v[92:93], v[132:133]
	v_pk_mul_f32 v[172:173], v[90:91], v[130:131]
	s_nop 0
	v_cvt_pk_bf16_f32 v172, v172, v173
	v_cvt_pk_bf16_f32 v173, v170, v171
	v_mov_b32_e32 v246, v172
	v_mov_b32_e32 v247, v173
	s_nop 1
	v_permlane16_swap_b32_e32 v244, v246
	v_permlane16_swap_b32_e32 v245, v247
	v_lshl_add_u64 v[234:235], v[162:163], 0, v[248:249]
	global_store_dwordx4 v[234:235], v[244:247], off offset:256
	v_or_b32_e32 v162, 16, v158
	v_ashrrev_i32_e32 v163, 31, v162
	v_lshlrev_b64 v[162:163], s12, v[162:163]
	v_pk_mul_f32 v[170:171], v[120:121], v[136:137]
	v_pk_mul_f32 v[172:173], v[118:119], v[134:135]
	v_lshl_add_u64 v[162:163], v[162:163], 1, v[160:161]
	v_cvt_pk_bf16_f32 v172, v172, v173
	v_cvt_pk_bf16_f32 v173, v170, v171
	v_mov_b32_e32 v226, v172
	v_mov_b32_e32 v227, v173
	v_pk_mul_f32 v[170:171], v[116:117], v[140:141]
	v_pk_mul_f32 v[172:173], v[114:115], v[138:139]
	s_nop 0
	v_cvt_pk_bf16_f32 v172, v172, v173
	v_cvt_pk_bf16_f32 v173, v170, v171
	v_mov_b32_e32 v228, v172
	v_mov_b32_e32 v229, v173
	s_nop 1
	v_permlane16_swap_b32_e32 v226, v228
	v_permlane16_swap_b32_e32 v227, v229
	v_lshl_add_u64 v[224:225], v[162:163], 0, v[248:249]
	global_store_dwordx4 v[224:225], v[226:229], off
	v_pk_mul_f32 v[170:171], v[88:89], v[144:145]
	v_pk_mul_f32 v[172:173], v[86:87], v[142:143]
	s_nop 0
	v_cvt_pk_bf16_f32 v172, v172, v173
	v_cvt_pk_bf16_f32 v173, v170, v171
	v_mov_b32_e32 v230, v172
	v_mov_b32_e32 v231, v173
	v_pk_mul_f32 v[170:171], v[84:85], v[132:133]
	v_pk_mul_f32 v[172:173], v[82:83], v[130:131]
	s_nop 0
	v_cvt_pk_bf16_f32 v172, v172, v173
	v_cvt_pk_bf16_f32 v173, v170, v171
	v_mov_b32_e32 v232, v172
	v_mov_b32_e32 v233, v173
	s_nop 1
	v_permlane16_swap_b32_e32 v230, v232
	v_permlane16_swap_b32_e32 v231, v233
	v_lshl_add_u64 v[222:223], v[162:163], 0, v[248:249]
	global_store_dwordx4 v[222:223], v[230:233], off offset:256
	v_or_b32_e32 v162, 32, v158
	v_ashrrev_i32_e32 v163, 31, v162
	v_lshlrev_b64 v[162:163], s12, v[162:163]
	v_pk_mul_f32 v[170:171], v[112:113], v[136:137]
	v_pk_mul_f32 v[172:173], v[110:111], v[134:135]
	v_lshl_add_u64 v[162:163], v[162:163], 1, v[160:161]
	v_cvt_pk_bf16_f32 v172, v172, v173
	v_cvt_pk_bf16_f32 v173, v170, v171
	v_mov_b32_e32 v240, v172
	v_mov_b32_e32 v241, v173
	v_pk_mul_f32 v[170:171], v[108:109], v[140:141]
	v_pk_mul_f32 v[172:173], v[106:107], v[138:139]
	s_nop 0
	v_cvt_pk_bf16_f32 v172, v172, v173
	v_cvt_pk_bf16_f32 v173, v170, v171
	v_mov_b32_e32 v242, v172
	v_mov_b32_e32 v243, v173
	s_nop 1
	v_permlane16_swap_b32_e32 v240, v242
	v_permlane16_swap_b32_e32 v241, v243
	v_lshl_add_u64 v[238:239], v[162:163], 0, v[248:249]
	global_store_dwordx4 v[238:239], v[240:243], off
	v_pk_mul_f32 v[170:171], v[80:81], v[144:145]
	v_pk_mul_f32 v[172:173], v[78:79], v[142:143]
	s_nop 0
	v_cvt_pk_bf16_f32 v172, v172, v173
	v_cvt_pk_bf16_f32 v173, v170, v171
	v_mov_b32_e32 v244, v172
	v_mov_b32_e32 v245, v173
	v_pk_mul_f32 v[170:171], v[76:77], v[132:133]
	v_pk_mul_f32 v[172:173], v[74:75], v[130:131]
	s_nop 0
	v_cvt_pk_bf16_f32 v172, v172, v173
	v_cvt_pk_bf16_f32 v173, v170, v171
	v_mov_b32_e32 v246, v172
	v_mov_b32_e32 v247, v173
	s_nop 1
	v_permlane16_swap_b32_e32 v244, v246
	v_permlane16_swap_b32_e32 v245, v247
	v_lshl_add_u64 v[234:235], v[162:163], 0, v[248:249]
	global_store_dwordx4 v[234:235], v[244:247], off offset:256
	v_or_b32_e32 v162, 48, v158
	v_ashrrev_i32_e32 v163, 31, v162
	v_lshlrev_b64 v[162:163], s12, v[162:163]
	v_pk_mul_f32 v[170:171], v[104:105], v[136:137]
	v_pk_mul_f32 v[172:173], v[102:103], v[134:135]
	v_lshl_add_u64 v[162:163], v[162:163], 1, v[160:161]
	v_cvt_pk_bf16_f32 v172, v172, v173
	v_cvt_pk_bf16_f32 v173, v170, v171
	v_mov_b32_e32 v226, v172
	v_mov_b32_e32 v227, v173
	v_pk_mul_f32 v[170:171], v[100:101], v[140:141]
	v_pk_mul_f32 v[172:173], v[98:99], v[138:139]
	s_nop 0
	v_cvt_pk_bf16_f32 v172, v172, v173
	v_cvt_pk_bf16_f32 v173, v170, v171
	v_mov_b32_e32 v228, v172
	v_mov_b32_e32 v229, v173
	s_nop 1
	v_permlane16_swap_b32_e32 v226, v228
	v_permlane16_swap_b32_e32 v227, v229
	v_lshl_add_u64 v[224:225], v[162:163], 0, v[248:249]
	global_store_dwordx4 v[224:225], v[226:229], off
	v_pk_mul_f32 v[170:171], v[72:73], v[144:145]
	v_pk_mul_f32 v[172:173], v[70:71], v[142:143]
	s_nop 0
	v_cvt_pk_bf16_f32 v172, v172, v173
	v_cvt_pk_bf16_f32 v173, v170, v171
	v_mov_b32_e32 v230, v172
	v_mov_b32_e32 v231, v173
	v_pk_mul_f32 v[170:171], v[68:69], v[132:133]
; __device__ __forceinline__ unsigned pk2(float lo, float hi) { f32x2_t v = {lo, hi}; bf16x2_t b = __builtin_convertvector(v, bf16x2_t); return __builtin_bit_cast(unsigned, b); }
; template <class Epi, class Sched, bool ALIGN_EPI = false, bool SP2 = false>
; __device__ __forceinline__ void gemm_phase(PG8_LAS unsigned char* lds, const Gemm g, const Sched& S, const Epi& E, const int wid) {
;     ...
;         if (!has_next) break;
;     __device__ __forceinline__ void operator()(const f32x4 (&acc)[2][2][4][2], const Unit& u, int wr, int wc, int fr, int fq) const {
;     ...
;         } else {
;             bf16_t* O = u.g == 0 ? KV : u.g == 2 ? MIX : QL; const int ldc = u.g == 0 ? 1024 : u.g == 2 ? DM : 2048; const float sc = u.g == 3 ? QSCALE : 1.f;
;             const int col0 = u.pn * BM + wc * 32 + 4 * fq;
;             f32x4 sv[2][2];
; #pragma unroll
;             for (int bj = 0; bj < 2; ++bj)
; #pragma unroll
;                 for (int n = 0; n < 2; ++n) { sv[bj][n] = (f32x4){sc, sc, sc, sc}; if (u.g == 2) sv[bj][n] = *(const f32x4*)(pool_scale + col0 + bj * HALF + n * 16); }
; #pragma unroll
;             for (int ai = 0; ai < 2; ++ai)
; #pragma unroll
;                 for (int m = 0; m < 4; ++m) { bf16_t* rowp = O + (size_t)(row0 + ai * HALF + m * 16) * ldc + col0;
; #pragma unroll
;                     for (int bj = 0; bj < 2; ++bj)
; #pragma unroll
;                         for (int n = 0; n < 2; ++n) { const f32x4 v = acc[ai][bj][m][n] * sv[bj][n]; u32x2 w; w.x = pk2(v[0], v[1]); w.y = pk2(v[2], v[3]); *(u32x2*)(rowp + bj * HALF + n * 16) = w; } }
	v_pk_mul_f32 v[172:173], v[66:67], v[130:131]
	s_nop 0
	v_cvt_pk_bf16_f32 v172, v172, v173
	v_cvt_pk_bf16_f32 v173, v170, v171
	v_mov_b32_e32 v232, v172
	v_mov_b32_e32 v233, v173
	s_nop 1
	v_permlane16_swap_b32_e32 v230, v232
	v_permlane16_swap_b32_e32 v231, v233
	v_lshl_add_u64 v[222:223], v[162:163], 0, v[248:249]
	global_store_dwordx4 v[222:223], v[230:233], off offset:256
	v_add_u32_e32 v162, 0x80, v158
	v_ashrrev_i32_e32 v163, 31, v162
	v_lshlrev_b64 v[162:163], s12, v[162:163]
	v_pk_mul_f32 v[170:171], v[64:65], v[136:137]
	v_pk_mul_f32 v[172:173], v[62:63], v[134:135]
	v_lshl_add_u64 v[162:163], v[162:163], 1, v[160:161]
	v_cvt_pk_bf16_f32 v172, v172, v173
	v_cvt_pk_bf16_f32 v173, v170, v171
	v_mov_b32_e32 v240, v172
	v_mov_b32_e32 v241, v173
	v_pk_mul_f32 v[170:171], v[60:61], v[140:141]
	v_pk_mul_f32 v[172:173], v[58:59], v[138:139]
	s_nop 0
	v_cvt_pk_bf16_f32 v172, v172, v173
	v_cvt_pk_bf16_f32 v173, v170, v171
	v_mov_b32_e32 v242, v172
	v_mov_b32_e32 v243, v173
	s_nop 1
	v_permlane16_swap_b32_e32 v240, v242
	v_permlane16_swap_b32_e32 v241, v243
	v_lshl_add_u64 v[238:239], v[162:163], 0, v[248:249]
	global_store_dwordx4 v[238:239], v[240:243], off
	v_pk_mul_f32 v[170:171], v[32:33], v[144:145]
	v_pk_mul_f32 v[172:173], v[30:31], v[142:143]
	s_nop 0
	v_cvt_pk_bf16_f32 v172, v172, v173
	v_cvt_pk_bf16_f32 v173, v170, v171
	v_mov_b32_e32 v244, v172
	v_mov_b32_e32 v245, v173
	v_pk_mul_f32 v[170:171], v[28:29], v[132:133]
	v_pk_mul_f32 v[172:173], v[26:27], v[130:131]
	s_nop 0
	v_cvt_pk_bf16_f32 v172, v172, v173
	v_cvt_pk_bf16_f32 v173, v170, v171
	v_mov_b32_e32 v246, v172
	v_mov_b32_e32 v247, v173
	s_nop 1
	v_permlane16_swap_b32_e32 v244, v246
	v_permlane16_swap_b32_e32 v245, v247
	v_lshl_add_u64 v[234:235], v[162:163], 0, v[248:249]
	global_store_dwordx4 v[234:235], v[244:247], off offset:256
	v_add_u32_e32 v162, 0x90, v158
	v_ashrrev_i32_e32 v163, 31, v162
	v_lshlrev_b64 v[162:163], s12, v[162:163]
	v_pk_mul_f32 v[170:171], v[56:57], v[136:137]
	v_pk_mul_f32 v[172:173], v[54:55], v[134:135]
	v_lshl_add_u64 v[162:163], v[162:163], 1, v[160:161]
	v_cvt_pk_bf16_f32 v172, v172, v173
	v_cvt_pk_bf16_f32 v173, v170, v171
	v_mov_b32_e32 v226, v172
	v_mov_b32_e32 v227, v173
	v_pk_mul_f32 v[170:171], v[52:53], v[140:141]
	v_pk_mul_f32 v[172:173], v[50:51], v[138:139]
	s_nop 0
	v_cvt_pk_bf16_f32 v172, v172, v173
	v_cvt_pk_bf16_f32 v173, v170, v171
	v_mov_b32_e32 v228, v172
	v_mov_b32_e32 v229, v173
	s_nop 1
	v_permlane16_swap_b32_e32 v226, v228
	v_permlane16_swap_b32_e32 v227, v229
	v_lshl_add_u64 v[224:225], v[162:163], 0, v[248:249]
	global_store_dwordx4 v[224:225], v[226:229], off
	v_pk_mul_f32 v[170:171], v[24:25], v[144:145]
	v_pk_mul_f32 v[172:173], v[22:23], v[142:143]
	s_nop 0
	v_cvt_pk_bf16_f32 v172, v172, v173
	v_cvt_pk_bf16_f32 v173, v170, v171
	v_mov_b32_e32 v230, v172
	v_mov_b32_e32 v231, v173
	v_pk_mul_f32 v[170:171], v[20:21], v[132:133]
	v_pk_mul_f32 v[172:173], v[18:19], v[130:131]
	s_nop 0
	v_cvt_pk_bf16_f32 v172, v172, v173
	v_cvt_pk_bf16_f32 v173, v170, v171
	v_mov_b32_e32 v232, v172
	v_mov_b32_e32 v233, v173
	s_nop 1
	v_permlane16_swap_b32_e32 v230, v232
	v_permlane16_swap_b32_e32 v231, v233
	v_lshl_add_u64 v[222:223], v[162:163], 0, v[248:249]
	global_store_dwordx4 v[222:223], v[230:233], off offset:256
	v_add_u32_e32 v162, 0xa0, v158
	v_ashrrev_i32_e32 v163, 31, v162
	v_lshlrev_b64 v[162:163], s12, v[162:163]
	v_pk_mul_f32 v[170:171], v[48:49], v[136:137]
	v_pk_mul_f32 v[172:173], v[46:47], v[134:135]
	v_lshl_add_u64 v[162:163], v[162:163], 1, v[160:161]
	v_cvt_pk_bf16_f32 v172, v172, v173
	v_cvt_pk_bf16_f32 v173, v170, v171
	v_mov_b32_e32 v240, v172
	v_mov_b32_e32 v241, v173
	v_pk_mul_f32 v[170:171], v[44:45], v[140:141]
	v_pk_mul_f32 v[172:173], v[42:43], v[138:139]
	v_add_u32_e32 v158, 0xb0, v158
	v_cvt_pk_bf16_f32 v172, v172, v173
	v_cvt_pk_bf16_f32 v173, v170, v171
	v_mov_b32_e32 v242, v172
	v_mov_b32_e32 v243, v173
	s_nop 1
	v_permlane16_swap_b32_e32 v240, v242
	v_permlane16_swap_b32_e32 v241, v243
	v_lshl_add_u64 v[238:239], v[162:163], 0, v[248:249]
	global_store_dwordx4 v[238:239], v[240:243], off
	v_pk_mul_f32 v[170:171], v[16:17], v[144:145]
	v_pk_mul_f32 v[172:173], v[14:15], v[142:143]
	v_ashrrev_i32_e32 v159, 31, v158
	v_cvt_pk_bf16_f32 v172, v172, v173
	v_cvt_pk_bf16_f32 v173, v170, v171
	v_mov_b32_e32 v244, v172
	v_mov_b32_e32 v245, v173
	v_pk_mul_f32 v[170:171], v[12:13], v[132:133]
	v_pk_mul_f32 v[172:173], v[10:11], v[130:131]
	v_lshlrev_b64 v[158:159], s12, v[158:159]
	v_pk_mul_f32 v[136:137], v[40:41], v[136:137]
	v_pk_mul_f32 v[134:135], v[38:39], v[134:135]
	v_cvt_pk_bf16_f32 v172, v172, v173
	v_cvt_pk_bf16_f32 v173, v170, v171
	v_lshl_add_u64 v[158:159], v[158:159], 1, v[160:161]
	v_cvt_pk_bf16_f32 v134, v134, v135
	v_cvt_pk_bf16_f32 v135, v136, v137
	v_mov_b32_e32 v246, v172
	v_mov_b32_e32 v247, v173
	s_nop 1
	v_permlane16_swap_b32_e32 v244, v246
	v_permlane16_swap_b32_e32 v245, v247
	v_lshl_add_u64 v[234:235], v[162:163], 0, v[248:249]
	global_store_dwordx4 v[234:235], v[244:247], off offset:256
	v_mov_b32_e32 v226, v134
	v_mov_b32_e32 v227, v135
	v_pk_mul_f32 v[134:135], v[36:37], v[140:141]
	v_pk_mul_f32 v[136:137], v[34:35], v[138:139]
	v_pk_mul_f32 v[132:133], v[4:5], v[132:133]
	v_cvt_pk_bf16_f32 v136, v136, v137
	v_cvt_pk_bf16_f32 v137, v134, v135
	v_mov_b32_e32 v228, v136
	v_mov_b32_e32 v229, v137
	s_nop 1
	v_permlane16_swap_b32_e32 v226, v228
	v_permlane16_swap_b32_e32 v227, v229
	v_lshl_add_u64 v[224:225], v[158:159], 0, v[248:249]
	global_store_dwordx4 v[224:225], v[226:229], off
	v_pk_mul_f32 v[134:135], v[8:9], v[144:145]
	v_pk_mul_f32 v[136:137], v[6:7], v[142:143]
	v_pk_mul_f32 v[130:131], v[2:3], v[130:131]
	v_cvt_pk_bf16_f32 v136, v136, v137
	v_cvt_pk_bf16_f32 v137, v134, v135
	v_cvt_pk_bf16_f32 v130, v130, v131
	v_cvt_pk_bf16_f32 v131, v132, v133
	v_mov_b32_e32 v230, v136
	v_mov_b32_e32 v231, v137
	v_mov_b32_e32 v232, v130
	v_mov_b32_e32 v233, v131
	s_nop 1
	v_permlane16_swap_b32_e32 v230, v232
	v_permlane16_swap_b32_e32 v231, v233
	v_lshl_add_u64 v[222:223], v[158:159], 0, v[248:249]
	global_store_dwordx4 v[222:223], v[230:233], off offset:256
	s_and_b64 vcc, exec, s[10:11]
	s_cbranch_vccnz .LBB0_851
